# cache-policy hints: nt additionally on the w_in GEMM (EpiIn) wide output stores
# speedup vs baseline: 1.0074x; 1.0074x over previous
.LBB0_489:
	s_cmp_gt_u32 s2, 16
	s_cbranch_scc0 .LBB0_493
	v_readlane_b32 s8, v254, 6
	v_readlane_b32 s9, v254, 7
	s_andn2_b64 vcc, exec, s[8:9]
	s_cbranch_vccnz .LBB0_492
	v_or_b32_e32 v130, 16, v190
	v_ashrrev_i32_e32 v191, 31, v190
	v_ashrrev_i32_e32 v131, 31, v130
	v_lshlrev_b64 v[128:129], 7, v[190:191]
	v_lshlrev_b64 v[130:131], 7, v[130:131]
	v_lshl_add_u64 v[128:129], v[180:181], 0, v[128:129]
	v_lshl_add_u64 v[130:131], v[180:181], 0, v[130:131]
	global_store_dwordx4 v[128:129], v[124:127], off nt
	global_store_dwordx4 v[128:129], v[120:123], off offset:16 nt
	global_store_dwordx4 v[130:131], v[108:111], off nt
	global_store_dwordx4 v[130:131], v[104:107], off offset:16 nt
	v_or_b32_e32 v130, 32, v190
	v_ashrrev_i32_e32 v131, 31, v130
	v_lshlrev_b64 v[130:131], 7, v[130:131]
	v_lshl_add_u64 v[130:131], v[180:181], 0, v[130:131]
	global_store_dwordx4 v[130:131], v[92:95], off nt
	global_store_dwordx4 v[130:131], v[88:91], off offset:16 nt
	v_or_b32_e32 v130, 48, v190
	v_ashrrev_i32_e32 v131, 31, v130
	v_lshlrev_b64 v[130:131], 7, v[130:131]
	v_lshl_add_u64 v[130:131], v[180:181], 0, v[130:131]
	s_mov_b64 s[8:9], 0x4000
	global_store_dwordx4 v[130:131], v[76:79], off nt
	global_store_dwordx4 v[130:131], v[72:75], off offset:16 nt
	v_lshl_add_u64 v[130:131], v[128:129], 0, s[8:9]
	s_movk_i32 s8, 0x4000
	v_add_co_u32_e32 v132, vcc, s8, v128
	s_mov_b64 s[8:9], 0x4800
	s_nop 0
	v_addc_co_u32_e32 v133, vcc, 0, v129, vcc
	global_store_dwordx4 v[132:133], v[60:63], off nt
	global_store_dwordx4 v[130:131], v[56:59], off offset:16 nt
	v_lshl_add_u64 v[130:131], v[128:129], 0, s[8:9]
	global_store_dwordx4 v[132:133], v[44:47], off offset:2048 nt
	global_store_dwordx4 v[130:131], v[40:43], off offset:16 nt
	s_mov_b64 s[8:9], 0x5000
	v_add_co_u32_e32 v132, vcc, 0x5000, v128
	v_lshl_add_u64 v[130:131], v[128:129], 0, s[8:9]
	s_nop 0
	v_addc_co_u32_e32 v133, vcc, 0, v129, vcc
	s_mov_b64 s[8:9], 0x5800
	global_store_dwordx4 v[132:133], v[28:31], off nt
	global_store_dwordx4 v[130:131], v[24:27], off offset:16 nt
	v_lshl_add_u64 v[128:129], v[128:129], 0, s[8:9]
	global_store_dwordx4 v[132:133], v[12:15], off offset:2048 nt
	global_store_dwordx4 v[128:129], v[8:11], off offset:16 nt

.LBB0_498:
	s_lshl_b64 s[16:17], s[82:83], 24
	v_ashrrev_i32_e32 v191, 31, v190
	v_lshl_add_u64 v[166:167], v[184:185], 0, s[16:17]
	v_lshlrev_b64 v[194:195], 8, v[190:191]
	v_cvt_pk_bf16_f32 v196, v124, v125
	v_cvt_pk_bf16_f32 v197, v126, v127
	v_cvt_pk_bf16_f32 v198, v120, v121
	v_cvt_pk_bf16_f32 v199, v122, v123
	v_lshl_add_u64 v[168:169], v[166:167], 0, v[194:195]
	global_store_dwordx4 v[168:169], v[196:199], off nt
	v_or_b32_e32 v168, 16, v190
	v_ashrrev_i32_e32 v169, 31, v168
	v_lshlrev_b64 v[196:197], 8, v[168:169]
	v_cvt_pk_bf16_f32 v198, v108, v109
	v_cvt_pk_bf16_f32 v199, v110, v111
	v_cvt_pk_bf16_f32 v200, v104, v105
	v_cvt_pk_bf16_f32 v201, v106, v107
	v_lshl_add_u64 v[168:169], v[166:167], 0, v[196:197]
	global_store_dwordx4 v[168:169], v[198:201], off nt
	v_or_b32_e32 v168, 32, v190
	v_ashrrev_i32_e32 v169, 31, v168
	v_lshlrev_b64 v[198:199], 8, v[168:169]
	v_cvt_pk_bf16_f32 v200, v92, v93
	v_cvt_pk_bf16_f32 v201, v94, v95
	v_cvt_pk_bf16_f32 v202, v88, v89
	v_cvt_pk_bf16_f32 v203, v90, v91
	v_lshl_add_u64 v[168:169], v[166:167], 0, v[198:199]
	global_store_dwordx4 v[168:169], v[200:203], off nt
	v_or_b32_e32 v168, 48, v190
	v_ashrrev_i32_e32 v169, 31, v168
	v_lshlrev_b64 v[200:201], 8, v[168:169]
	v_ashrrev_i32_e32 v193, 31, v192
	v_cvt_pk_bf16_f32 v202, v76, v77
	v_cvt_pk_bf16_f32 v203, v78, v79
	v_cvt_pk_bf16_f32 v204, v72, v73
	v_cvt_pk_bf16_f32 v205, v74, v75
	v_lshl_add_u64 v[168:169], v[166:167], 0, v[200:201]
	v_lshlrev_b64 v[192:193], 8, v[192:193]
	global_store_dwordx4 v[168:169], v[202:205], off nt
	v_lshl_add_u64 v[168:169], v[166:167], 0, v[192:193]
	s_mov_b64 s[16:17], 0x9000
	v_cvt_pk_bf16_f32 v202, v60, v61
	v_cvt_pk_bf16_f32 v203, v62, v63
	v_cvt_pk_bf16_f32 v204, v56, v57
	v_cvt_pk_bf16_f32 v205, v58, v59
	global_store_dwordx4 v[168:169], v[202:205], off nt
	v_cvt_pk_bf16_f32 v206, v40, v41
	v_cvt_pk_bf16_f32 v207, v42, v43
	v_lshl_add_u64 v[202:203], v[194:195], 0, s[16:17]
	v_cvt_pk_bf16_f32 v204, v44, v45
	v_cvt_pk_bf16_f32 v205, v46, v47
	v_lshl_add_u64 v[168:169], v[166:167], 0, v[202:203]
	s_mov_b64 s[16:17], 0xa000
	global_store_dwordx4 v[168:169], v[204:207], off nt
	v_cvt_pk_bf16_f32 v232, v28, v29
	v_cvt_pk_bf16_f32 v233, v30, v31
	v_lshl_add_u64 v[204:205], v[194:195], 0, s[16:17]
	s_mov_b64 s[16:17], 0xb000
	v_cvt_pk_bf16_f32 v234, v24, v25
	v_cvt_pk_bf16_f32 v235, v26, v27
	v_lshl_add_u64 v[168:169], v[166:167], 0, v[204:205]
	v_lshl_add_u64 v[206:207], v[194:195], 0, s[16:17]
	global_store_dwordx4 v[168:169], v[232:235], off nt
	v_lshl_add_u64 v[166:167], v[166:167], 0, v[206:207]
	s_andn2_b64 vcc, exec, s[8:9]
	v_cvt_pk_bf16_f32 v232, v12, v13
	v_cvt_pk_bf16_f32 v233, v14, v15
	v_cvt_pk_bf16_f32 v234, v8, v9
	v_cvt_pk_bf16_f32 v235, v10, v11
	global_store_dwordx4 v[166:167], v[232:235], off nt
	s_cbranch_vccnz .LBB0_500
	s_add_i32 s82, s82, 1
	s_lshl_b64 s[8:9], s[82:83], 24
	v_lshl_add_u64 v[166:167], v[184:185], 0, s[8:9]
	v_lshl_add_u64 v[168:169], v[166:167], 0, v[194:195]
	global_store_dwordx4 v[168:169], v[156:159], off nt
	s_nop 1
	v_lshl_add_u64 v[156:157], v[166:167], 0, v[196:197]
	global_store_dwordx4 v[156:157], v[152:155], off nt
	s_nop 1
	v_lshl_add_u64 v[152:153], v[166:167], 0, v[198:199]
	global_store_dwordx4 v[152:153], v[148:151], off nt
	s_nop 1
	v_lshl_add_u64 v[148:149], v[166:167], 0, v[200:201]
	global_store_dwordx4 v[148:149], v[144:147], off nt
	s_nop 1
	v_lshl_add_u64 v[144:145], v[166:167], 0, v[192:193]
	global_store_dwordx4 v[144:145], v[140:143], off nt
	s_nop 1
	v_lshl_add_u64 v[140:141], v[166:167], 0, v[202:203]
	global_store_dwordx4 v[140:141], v[136:139], off nt
	s_nop 1
	v_lshl_add_u64 v[136:137], v[166:167], 0, v[204:205]
	global_store_dwordx4 v[136:137], v[132:135], off nt
	s_nop 1
	v_lshl_add_u64 v[132:133], v[166:167], 0, v[206:207]
	global_store_dwordx4 v[132:133], v[128:131], off nt

.LBB0_503:
	s_lshl_b32 s1, s2, 1
	s_and_b32 s1, s1, -4
	s_lshr_b32 s1, 0x2146530, s1
	s_lshl_b32 s1, s1, 26
	s_and_b32 s1, s1, 0x1c000000
	s_add_u32 s1, s26, s1
	s_addc_u32 s9, s27, 0
	s_lshl_b32 s2, s2, 9
	s_and_b32 s2, s2, 0x200
	s_add_u32 s8, s1, s2
	s_addc_u32 s9, s9, 0
	v_ashrrev_i32_e32 v191, 31, v190
	v_lshl_add_u64 v[128:129], v[178:179], 1, s[8:9]
	v_lshlrev_b64 v[130:131], 10, v[190:191]
	v_cvt_pk_bf16_f32 v124, v124, v125
	v_cvt_pk_bf16_f32 v125, v126, v127
	v_cvt_pk_bf16_f32 v126, v120, v121
	v_cndmask_b32_e64 v120, 0, 1, s[16:17]
	v_lshl_add_u64 v[130:131], v[128:129], 0, v[130:131]
	v_cvt_pk_bf16_f32 v127, v122, v123
	v_cmp_ne_u32_e64 s[8:9], 1, v120
	s_andn2_b64 vcc, exec, s[16:17]
	global_store_dwordx4 v[130:131], v[124:127], off nt
	s_cbranch_vccnz .LBB0_505
	v_mul_f32_e32 v120, v116, v116
	v_mul_f32_e32 v121, v117, v117
	v_mul_f32_e32 v122, v118, v118
	v_mul_f32_e32 v123, v119, v119
	v_fmamk_f32 v120, v120, 0xbdd2d3e8, v209
	v_fmamk_f32 v121, v121, 0xbdd2d3e8, v209
	v_fmamk_f32 v122, v122, 0xbdd2d3e8, v209
	v_fmamk_f32 v123, v123, 0xbdd2d3e8, v209
	v_mul_f32_e32 v120, v116, v120
	v_mul_f32_e32 v121, v117, v121
	v_mul_f32_e32 v122, v118, v122
	v_mul_f32_e32 v123, v119, v123
	v_exp_f32_e32 v120, v120
	v_exp_f32_e32 v121, v121
	v_exp_f32_e32 v122, v122
	v_exp_f32_e32 v123, v123
	v_add_f32_e32 v120, 1.0, v120
	v_add_f32_e32 v121, 1.0, v121
	v_add_f32_e32 v122, 1.0, v122
	v_add_f32_e32 v123, 1.0, v123
	v_rcp_f32_e32 v120, v120
	v_rcp_f32_e32 v121, v121
	v_rcp_f32_e32 v122, v122
	v_rcp_f32_e32 v123, v123
	v_pk_mul_f32 v[116:117], v[116:117], v[120:121]
	v_mul_f32_e32 v120, v112, v112
	v_pk_mul_f32 v[118:119], v[118:119], v[122:123]
	v_mul_f32_e32 v121, v113, v113
	v_mul_f32_e32 v122, v114, v114
	v_mul_f32_e32 v123, v115, v115
	v_fmamk_f32 v120, v120, 0xbdd2d3e8, v209
	v_fmamk_f32 v121, v121, 0xbdd2d3e8, v209
	v_fmamk_f32 v122, v122, 0xbdd2d3e8, v209
	v_fmamk_f32 v123, v123, 0xbdd2d3e8, v209
	v_mul_f32_e32 v120, v112, v120
	v_mul_f32_e32 v121, v113, v121
	v_mul_f32_e32 v122, v114, v122
	v_mul_f32_e32 v123, v115, v123
	v_exp_f32_e32 v120, v120
	v_exp_f32_e32 v121, v121
	v_exp_f32_e32 v122, v122
	v_exp_f32_e32 v123, v123
	v_add_f32_e32 v120, 1.0, v120
	v_add_f32_e32 v121, 1.0, v121
	v_add_f32_e32 v122, 1.0, v122
	v_add_f32_e32 v123, 1.0, v123
	v_rcp_f32_e32 v120, v120
	v_rcp_f32_e32 v121, v121
	v_rcp_f32_e32 v122, v122
	v_rcp_f32_e32 v123, v123
	v_pk_mul_f32 v[112:113], v[112:113], v[120:121]
	v_pk_mul_f32 v[114:115], v[114:115], v[122:123]
.LBB0_505:
	v_cvt_pk_bf16_f32 v116, v116, v117
	v_cvt_pk_bf16_f32 v117, v118, v119
	v_cvt_pk_bf16_f32 v118, v112, v113
	v_cvt_pk_bf16_f32 v119, v114, v115
	s_and_b64 vcc, exec, s[8:9]
	global_store_dwordx4 v[130:131], v[116:119], off offset:256 nt
	s_cbranch_vccnz .LBB0_507
	v_mul_f32_e32 v112, v108, v108
	v_mul_f32_e32 v113, v109, v109
	v_mul_f32_e32 v114, v110, v110
	v_mul_f32_e32 v115, v111, v111
	v_fmamk_f32 v112, v112, 0xbdd2d3e8, v209
	v_fmamk_f32 v113, v113, 0xbdd2d3e8, v209
	v_fmamk_f32 v114, v114, 0xbdd2d3e8, v209
	v_fmamk_f32 v115, v115, 0xbdd2d3e8, v209
	v_mul_f32_e32 v112, v108, v112
	v_mul_f32_e32 v113, v109, v113
	v_mul_f32_e32 v114, v110, v114
	v_mul_f32_e32 v115, v111, v115
	v_exp_f32_e32 v112, v112
	v_exp_f32_e32 v113, v113
	v_exp_f32_e32 v114, v114
	v_exp_f32_e32 v115, v115
	v_add_f32_e32 v112, 1.0, v112
	v_add_f32_e32 v113, 1.0, v113
	v_add_f32_e32 v114, 1.0, v114
	v_add_f32_e32 v115, 1.0, v115
	v_rcp_f32_e32 v112, v112
	v_rcp_f32_e32 v113, v113
	v_rcp_f32_e32 v114, v114
	v_rcp_f32_e32 v115, v115
	v_pk_mul_f32 v[108:109], v[108:109], v[112:113]
	v_mul_f32_e32 v112, v104, v104
	v_pk_mul_f32 v[110:111], v[110:111], v[114:115]
	v_mul_f32_e32 v113, v105, v105
	v_mul_f32_e32 v114, v106, v106
	v_mul_f32_e32 v115, v107, v107
	v_fmamk_f32 v112, v112, 0xbdd2d3e8, v209
	v_fmamk_f32 v113, v113, 0xbdd2d3e8, v209
	v_fmamk_f32 v114, v114, 0xbdd2d3e8, v209
	v_fmamk_f32 v115, v115, 0xbdd2d3e8, v209
	v_mul_f32_e32 v112, v104, v112
	v_mul_f32_e32 v113, v105, v113
	v_mul_f32_e32 v114, v106, v114
	v_mul_f32_e32 v115, v107, v115
	v_exp_f32_e32 v112, v112
	v_exp_f32_e32 v113, v113
	v_exp_f32_e32 v114, v114
	v_exp_f32_e32 v115, v115
	v_add_f32_e32 v112, 1.0, v112
	v_add_f32_e32 v113, 1.0, v113
	v_add_f32_e32 v114, 1.0, v114
	v_add_f32_e32 v115, 1.0, v115
	v_rcp_f32_e32 v112, v112
	v_rcp_f32_e32 v113, v113
	v_rcp_f32_e32 v114, v114
	v_rcp_f32_e32 v115, v115
	v_pk_mul_f32 v[104:105], v[104:105], v[112:113]
	v_pk_mul_f32 v[106:107], v[106:107], v[114:115]
.LBB0_507:
	v_or_b32_e32 v112, 16, v190
	v_ashrrev_i32_e32 v113, 31, v112
	v_lshlrev_b64 v[112:113], 10, v[112:113]
	v_lshl_add_u64 v[112:113], v[128:129], 0, v[112:113]
	v_cvt_pk_bf16_f32 v108, v108, v109
	v_cvt_pk_bf16_f32 v109, v110, v111
	v_cvt_pk_bf16_f32 v110, v104, v105
	v_cvt_pk_bf16_f32 v111, v106, v107
	s_and_b64 vcc, exec, s[8:9]
	global_store_dwordx4 v[112:113], v[108:111], off nt
	s_cbranch_vccnz .LBB0_509
	v_mul_f32_e32 v104, v100, v100
	v_mul_f32_e32 v105, v101, v101
	v_mul_f32_e32 v106, v102, v102
	v_mul_f32_e32 v107, v103, v103
	v_fmamk_f32 v104, v104, 0xbdd2d3e8, v209
	v_fmamk_f32 v105, v105, 0xbdd2d3e8, v209
	v_fmamk_f32 v106, v106, 0xbdd2d3e8, v209
	v_fmamk_f32 v107, v107, 0xbdd2d3e8, v209
	v_mul_f32_e32 v104, v100, v104
	v_mul_f32_e32 v105, v101, v105
	v_mul_f32_e32 v106, v102, v106
	v_mul_f32_e32 v107, v103, v107
	v_exp_f32_e32 v104, v104
	v_exp_f32_e32 v105, v105
	v_exp_f32_e32 v106, v106
	v_exp_f32_e32 v107, v107
	v_add_f32_e32 v104, 1.0, v104
	v_add_f32_e32 v105, 1.0, v105
	v_add_f32_e32 v106, 1.0, v106
	v_add_f32_e32 v107, 1.0, v107
	v_rcp_f32_e32 v104, v104
	v_rcp_f32_e32 v105, v105
	v_rcp_f32_e32 v106, v106
	v_rcp_f32_e32 v107, v107
	v_pk_mul_f32 v[100:101], v[100:101], v[104:105]
	v_mul_f32_e32 v104, v96, v96
	v_pk_mul_f32 v[102:103], v[102:103], v[106:107]
	v_mul_f32_e32 v105, v97, v97
	v_mul_f32_e32 v106, v98, v98
	v_mul_f32_e32 v107, v99, v99
	v_fmamk_f32 v104, v104, 0xbdd2d3e8, v209
	v_fmamk_f32 v105, v105, 0xbdd2d3e8, v209
	v_fmamk_f32 v106, v106, 0xbdd2d3e8, v209
	v_fmamk_f32 v107, v107, 0xbdd2d3e8, v209
	v_mul_f32_e32 v104, v96, v104
	v_mul_f32_e32 v105, v97, v105
	v_mul_f32_e32 v106, v98, v106
	v_mul_f32_e32 v107, v99, v107
	v_exp_f32_e32 v104, v104
	v_exp_f32_e32 v105, v105
	v_exp_f32_e32 v106, v106
	v_exp_f32_e32 v107, v107
	v_add_f32_e32 v104, 1.0, v104
	v_add_f32_e32 v105, 1.0, v105
	v_add_f32_e32 v106, 1.0, v106
	v_add_f32_e32 v107, 1.0, v107
	v_rcp_f32_e32 v104, v104
	v_rcp_f32_e32 v105, v105
	v_rcp_f32_e32 v106, v106
	v_rcp_f32_e32 v107, v107
	v_pk_mul_f32 v[96:97], v[96:97], v[104:105]
	v_pk_mul_f32 v[98:99], v[98:99], v[106:107]
.LBB0_509:
	v_cvt_pk_bf16_f32 v100, v100, v101
	v_cvt_pk_bf16_f32 v101, v102, v103
	v_cvt_pk_bf16_f32 v102, v96, v97
	v_cvt_pk_bf16_f32 v103, v98, v99
	s_and_b64 vcc, exec, s[8:9]
	global_store_dwordx4 v[112:113], v[100:103], off offset:256 nt
	s_cbranch_vccnz .LBB0_511
	v_mul_f32_e32 v96, v92, v92
	v_mul_f32_e32 v97, v93, v93
	v_mul_f32_e32 v98, v94, v94
	v_mul_f32_e32 v99, v95, v95
	v_fmamk_f32 v96, v96, 0xbdd2d3e8, v209
	v_fmamk_f32 v97, v97, 0xbdd2d3e8, v209
	v_fmamk_f32 v98, v98, 0xbdd2d3e8, v209
	v_fmamk_f32 v99, v99, 0xbdd2d3e8, v209
	v_mul_f32_e32 v96, v92, v96
	v_mul_f32_e32 v97, v93, v97
	v_mul_f32_e32 v98, v94, v98
	v_mul_f32_e32 v99, v95, v99
	v_exp_f32_e32 v96, v96
	v_exp_f32_e32 v97, v97
	v_exp_f32_e32 v98, v98
	v_exp_f32_e32 v99, v99
	v_add_f32_e32 v96, 1.0, v96
	v_add_f32_e32 v97, 1.0, v97
	v_add_f32_e32 v98, 1.0, v98
	v_add_f32_e32 v99, 1.0, v99
	v_rcp_f32_e32 v96, v96
	v_rcp_f32_e32 v97, v97
	v_rcp_f32_e32 v98, v98
	v_rcp_f32_e32 v99, v99
	v_pk_mul_f32 v[92:93], v[92:93], v[96:97]
	v_mul_f32_e32 v96, v88, v88
	v_pk_mul_f32 v[94:95], v[94:95], v[98:99]
	v_mul_f32_e32 v97, v89, v89
	v_mul_f32_e32 v98, v90, v90
	v_mul_f32_e32 v99, v91, v91
	v_fmamk_f32 v96, v96, 0xbdd2d3e8, v209
	v_fmamk_f32 v97, v97, 0xbdd2d3e8, v209
	v_fmamk_f32 v98, v98, 0xbdd2d3e8, v209
	v_fmamk_f32 v99, v99, 0xbdd2d3e8, v209
	v_mul_f32_e32 v96, v88, v96
	v_mul_f32_e32 v97, v89, v97
	v_mul_f32_e32 v98, v90, v98
	v_mul_f32_e32 v99, v91, v99
	v_exp_f32_e32 v96, v96
	v_exp_f32_e32 v97, v97
	v_exp_f32_e32 v98, v98
	v_exp_f32_e32 v99, v99
	v_add_f32_e32 v96, 1.0, v96
	v_add_f32_e32 v97, 1.0, v97
	v_add_f32_e32 v98, 1.0, v98
	v_add_f32_e32 v99, 1.0, v99
	v_rcp_f32_e32 v96, v96
	v_rcp_f32_e32 v97, v97
	v_rcp_f32_e32 v98, v98
	v_rcp_f32_e32 v99, v99
	v_pk_mul_f32 v[88:89], v[88:89], v[96:97]
	v_pk_mul_f32 v[90:91], v[90:91], v[98:99]
.LBB0_511:
	v_or_b32_e32 v96, 32, v190
	v_ashrrev_i32_e32 v97, 31, v96
	v_lshlrev_b64 v[96:97], 10, v[96:97]
	v_lshl_add_u64 v[96:97], v[128:129], 0, v[96:97]
	v_cvt_pk_bf16_f32 v92, v92, v93
	v_cvt_pk_bf16_f32 v93, v94, v95
	v_cvt_pk_bf16_f32 v94, v88, v89
	v_cvt_pk_bf16_f32 v95, v90, v91
	s_and_b64 vcc, exec, s[8:9]
	global_store_dwordx4 v[96:97], v[92:95], off nt
	s_cbranch_vccnz .LBB0_513
	v_mul_f32_e32 v88, v84, v84
	v_mul_f32_e32 v89, v85, v85
	v_mul_f32_e32 v90, v86, v86
	v_mul_f32_e32 v91, v87, v87
	v_fmamk_f32 v88, v88, 0xbdd2d3e8, v209
	v_fmamk_f32 v89, v89, 0xbdd2d3e8, v209
	v_fmamk_f32 v90, v90, 0xbdd2d3e8, v209
	v_fmamk_f32 v91, v91, 0xbdd2d3e8, v209
	v_mul_f32_e32 v88, v84, v88
	v_mul_f32_e32 v89, v85, v89
	v_mul_f32_e32 v90, v86, v90
	v_mul_f32_e32 v91, v87, v91
	v_exp_f32_e32 v88, v88
	v_exp_f32_e32 v89, v89
	v_exp_f32_e32 v90, v90
	v_exp_f32_e32 v91, v91
	v_add_f32_e32 v88, 1.0, v88
	v_add_f32_e32 v89, 1.0, v89
	v_add_f32_e32 v90, 1.0, v90
	v_add_f32_e32 v91, 1.0, v91
	v_rcp_f32_e32 v88, v88
	v_rcp_f32_e32 v89, v89
	v_rcp_f32_e32 v90, v90
	v_rcp_f32_e32 v91, v91
	v_pk_mul_f32 v[84:85], v[84:85], v[88:89]
	v_mul_f32_e32 v88, v80, v80
	v_pk_mul_f32 v[86:87], v[86:87], v[90:91]
	v_mul_f32_e32 v89, v81, v81
	v_mul_f32_e32 v90, v82, v82
	v_mul_f32_e32 v91, v83, v83
	v_fmamk_f32 v88, v88, 0xbdd2d3e8, v209
	v_fmamk_f32 v89, v89, 0xbdd2d3e8, v209
	v_fmamk_f32 v90, v90, 0xbdd2d3e8, v209
	v_fmamk_f32 v91, v91, 0xbdd2d3e8, v209
	v_mul_f32_e32 v88, v80, v88
	v_mul_f32_e32 v89, v81, v89
	v_mul_f32_e32 v90, v82, v90
	v_mul_f32_e32 v91, v83, v91
	v_exp_f32_e32 v88, v88
	v_exp_f32_e32 v89, v89
	v_exp_f32_e32 v90, v90
	v_exp_f32_e32 v91, v91
	v_add_f32_e32 v88, 1.0, v88
	v_add_f32_e32 v89, 1.0, v89
	v_add_f32_e32 v90, 1.0, v90
	v_add_f32_e32 v91, 1.0, v91
	v_rcp_f32_e32 v88, v88
	v_rcp_f32_e32 v89, v89
	v_rcp_f32_e32 v90, v90
	v_rcp_f32_e32 v91, v91
	v_pk_mul_f32 v[80:81], v[80:81], v[88:89]
	v_pk_mul_f32 v[82:83], v[82:83], v[90:91]
.LBB0_513:
	v_cvt_pk_bf16_f32 v84, v84, v85
	v_cvt_pk_bf16_f32 v85, v86, v87
	v_cvt_pk_bf16_f32 v86, v80, v81
	v_cvt_pk_bf16_f32 v87, v82, v83
	s_and_b64 vcc, exec, s[8:9]
	global_store_dwordx4 v[96:97], v[84:87], off offset:256 nt
	s_cbranch_vccnz .LBB0_515
	v_mul_f32_e32 v80, v76, v76
	v_mul_f32_e32 v81, v77, v77
	v_mul_f32_e32 v82, v78, v78
	v_mul_f32_e32 v83, v79, v79
	v_fmamk_f32 v80, v80, 0xbdd2d3e8, v209
	v_fmamk_f32 v81, v81, 0xbdd2d3e8, v209
	v_fmamk_f32 v82, v82, 0xbdd2d3e8, v209
	v_fmamk_f32 v83, v83, 0xbdd2d3e8, v209
	v_mul_f32_e32 v80, v76, v80
	v_mul_f32_e32 v81, v77, v81
	v_mul_f32_e32 v82, v78, v82
	v_mul_f32_e32 v83, v79, v83
	v_exp_f32_e32 v80, v80
	v_exp_f32_e32 v81, v81
	v_exp_f32_e32 v82, v82
	v_exp_f32_e32 v83, v83
	v_add_f32_e32 v80, 1.0, v80
	v_add_f32_e32 v81, 1.0, v81
	v_add_f32_e32 v82, 1.0, v82
	v_add_f32_e32 v83, 1.0, v83
	v_rcp_f32_e32 v80, v80
	v_rcp_f32_e32 v81, v81
	v_rcp_f32_e32 v82, v82
	v_rcp_f32_e32 v83, v83
	v_pk_mul_f32 v[76:77], v[76:77], v[80:81]
	v_mul_f32_e32 v80, v72, v72
	v_pk_mul_f32 v[78:79], v[78:79], v[82:83]
	v_mul_f32_e32 v81, v73, v73
	v_mul_f32_e32 v82, v74, v74
	v_mul_f32_e32 v83, v75, v75
	v_fmamk_f32 v80, v80, 0xbdd2d3e8, v209
	v_fmamk_f32 v81, v81, 0xbdd2d3e8, v209
	v_fmamk_f32 v82, v82, 0xbdd2d3e8, v209
	v_fmamk_f32 v83, v83, 0xbdd2d3e8, v209
	v_mul_f32_e32 v80, v72, v80
	v_mul_f32_e32 v81, v73, v81
	v_mul_f32_e32 v82, v74, v82
	v_mul_f32_e32 v83, v75, v83
	v_exp_f32_e32 v80, v80
	v_exp_f32_e32 v81, v81
	v_exp_f32_e32 v82, v82
	v_exp_f32_e32 v83, v83
	v_add_f32_e32 v80, 1.0, v80
	v_add_f32_e32 v81, 1.0, v81
	v_add_f32_e32 v82, 1.0, v82
	v_add_f32_e32 v83, 1.0, v83
	v_rcp_f32_e32 v80, v80
	v_rcp_f32_e32 v81, v81
	v_rcp_f32_e32 v82, v82
	v_rcp_f32_e32 v83, v83
	v_pk_mul_f32 v[72:73], v[72:73], v[80:81]
	v_pk_mul_f32 v[74:75], v[74:75], v[82:83]
.LBB0_515:
	v_or_b32_e32 v80, 48, v190
	v_ashrrev_i32_e32 v81, 31, v80
	v_lshlrev_b64 v[80:81], 10, v[80:81]
	v_lshl_add_u64 v[80:81], v[128:129], 0, v[80:81]
	v_cvt_pk_bf16_f32 v76, v76, v77
	v_cvt_pk_bf16_f32 v77, v78, v79
	v_cvt_pk_bf16_f32 v78, v72, v73
	v_cvt_pk_bf16_f32 v79, v74, v75
	s_and_b64 vcc, exec, s[8:9]
	global_store_dwordx4 v[80:81], v[76:79], off nt
	s_cbranch_vccnz .LBB0_517
	v_mul_f32_e32 v72, v68, v68
	v_mul_f32_e32 v73, v69, v69
	v_mul_f32_e32 v74, v70, v70
	v_mul_f32_e32 v75, v71, v71
	v_fmamk_f32 v72, v72, 0xbdd2d3e8, v209
	v_fmamk_f32 v73, v73, 0xbdd2d3e8, v209
	v_fmamk_f32 v74, v74, 0xbdd2d3e8, v209
	v_fmamk_f32 v75, v75, 0xbdd2d3e8, v209
	v_mul_f32_e32 v72, v68, v72
	v_mul_f32_e32 v73, v69, v73
	v_mul_f32_e32 v74, v70, v74
	v_mul_f32_e32 v75, v71, v75
	v_exp_f32_e32 v72, v72
	v_exp_f32_e32 v73, v73
	v_exp_f32_e32 v74, v74
	v_exp_f32_e32 v75, v75
	v_add_f32_e32 v72, 1.0, v72
	v_add_f32_e32 v73, 1.0, v73
	v_add_f32_e32 v74, 1.0, v74
	v_add_f32_e32 v75, 1.0, v75
	v_rcp_f32_e32 v72, v72
	v_rcp_f32_e32 v73, v73
	v_rcp_f32_e32 v74, v74
	v_rcp_f32_e32 v75, v75
	v_pk_mul_f32 v[68:69], v[68:69], v[72:73]
	v_mul_f32_e32 v72, v64, v64
	v_pk_mul_f32 v[70:71], v[70:71], v[74:75]
	v_mul_f32_e32 v73, v65, v65
	v_mul_f32_e32 v74, v66, v66
	v_mul_f32_e32 v75, v67, v67
	v_fmamk_f32 v72, v72, 0xbdd2d3e8, v209
	v_fmamk_f32 v73, v73, 0xbdd2d3e8, v209
	v_fmamk_f32 v74, v74, 0xbdd2d3e8, v209
	v_fmamk_f32 v75, v75, 0xbdd2d3e8, v209
	v_mul_f32_e32 v72, v64, v72
	v_mul_f32_e32 v73, v65, v73
	v_mul_f32_e32 v74, v66, v74
	v_mul_f32_e32 v75, v67, v75
	v_exp_f32_e32 v72, v72
	v_exp_f32_e32 v73, v73
	v_exp_f32_e32 v74, v74
	v_exp_f32_e32 v75, v75
	v_add_f32_e32 v72, 1.0, v72
	v_add_f32_e32 v73, 1.0, v73
	v_add_f32_e32 v74, 1.0, v74
	v_add_f32_e32 v75, 1.0, v75
	v_rcp_f32_e32 v72, v72
	v_rcp_f32_e32 v73, v73
	v_rcp_f32_e32 v74, v74
	v_rcp_f32_e32 v75, v75
	v_pk_mul_f32 v[64:65], v[64:65], v[72:73]
	v_pk_mul_f32 v[66:67], v[66:67], v[74:75]
.LBB0_517:
	v_cvt_pk_bf16_f32 v68, v68, v69
	v_cvt_pk_bf16_f32 v69, v70, v71
	v_cvt_pk_bf16_f32 v70, v64, v65
	v_cvt_pk_bf16_f32 v71, v66, v67
	s_and_b64 vcc, exec, s[8:9]
	global_store_dwordx4 v[80:81], v[68:71], off offset:256 nt
	s_cbranch_vccnz .LBB0_519
	v_mul_f32_e32 v64, v60, v60
	v_mul_f32_e32 v65, v61, v61
	v_mul_f32_e32 v66, v62, v62
	v_mul_f32_e32 v67, v63, v63
	v_fmamk_f32 v64, v64, 0xbdd2d3e8, v209
	v_fmamk_f32 v65, v65, 0xbdd2d3e8, v209
	v_fmamk_f32 v66, v66, 0xbdd2d3e8, v209
	v_fmamk_f32 v67, v67, 0xbdd2d3e8, v209
	v_mul_f32_e32 v64, v60, v64
	v_mul_f32_e32 v65, v61, v65
	v_mul_f32_e32 v66, v62, v66
	v_mul_f32_e32 v67, v63, v67
	v_exp_f32_e32 v64, v64
	v_exp_f32_e32 v65, v65
	v_exp_f32_e32 v66, v66
	v_exp_f32_e32 v67, v67
	v_add_f32_e32 v64, 1.0, v64
	v_add_f32_e32 v65, 1.0, v65
	v_add_f32_e32 v66, 1.0, v66
	v_add_f32_e32 v67, 1.0, v67
	v_rcp_f32_e32 v64, v64
	v_rcp_f32_e32 v65, v65
	v_rcp_f32_e32 v66, v66
	v_rcp_f32_e32 v67, v67
	v_pk_mul_f32 v[60:61], v[60:61], v[64:65]
	v_mul_f32_e32 v64, v56, v56
	v_pk_mul_f32 v[62:63], v[62:63], v[66:67]
	v_mul_f32_e32 v65, v57, v57
	v_mul_f32_e32 v66, v58, v58
	v_mul_f32_e32 v67, v59, v59
	v_fmamk_f32 v64, v64, 0xbdd2d3e8, v209
	v_fmamk_f32 v65, v65, 0xbdd2d3e8, v209
	v_fmamk_f32 v66, v66, 0xbdd2d3e8, v209
	v_fmamk_f32 v67, v67, 0xbdd2d3e8, v209
	v_mul_f32_e32 v64, v56, v64
	v_mul_f32_e32 v65, v57, v65
	v_mul_f32_e32 v66, v58, v66
	v_mul_f32_e32 v67, v59, v67
	v_exp_f32_e32 v64, v64
	v_exp_f32_e32 v65, v65
	v_exp_f32_e32 v66, v66
	v_exp_f32_e32 v67, v67
	v_add_f32_e32 v64, 1.0, v64
	v_add_f32_e32 v65, 1.0, v65
	v_add_f32_e32 v66, 1.0, v66
	v_add_f32_e32 v67, 1.0, v67
	v_rcp_f32_e32 v64, v64
	v_rcp_f32_e32 v65, v65
	v_rcp_f32_e32 v66, v66
	v_rcp_f32_e32 v67, v67
	v_pk_mul_f32 v[56:57], v[56:57], v[64:65]
	v_pk_mul_f32 v[58:59], v[58:59], v[66:67]
.LBB0_519:
	v_lshlrev_b64 v[64:65], 10, v[190:191]
	v_lshl_add_u64 v[64:65], v[128:129], 0, v[64:65]
	v_cvt_pk_bf16_f32 v60, v60, v61
	v_cvt_pk_bf16_f32 v61, v62, v63
	v_cvt_pk_bf16_f32 v62, v56, v57
	v_add_co_u32_e32 v56, vcc, 0x20000, v64
	v_cvt_pk_bf16_f32 v63, v58, v59
	s_nop 0
	v_addc_co_u32_e32 v57, vcc, 0, v65, vcc
	s_and_b64 vcc, exec, s[8:9]
	global_store_dwordx4 v[56:57], v[60:63], off nt
	s_cbranch_vccnz .LBB0_521
	v_mul_f32_e32 v56, v52, v52
	v_mul_f32_e32 v57, v53, v53
	v_mul_f32_e32 v58, v54, v54
	v_mul_f32_e32 v59, v55, v55
	v_fmamk_f32 v56, v56, 0xbdd2d3e8, v209
	v_fmamk_f32 v57, v57, 0xbdd2d3e8, v209
	v_fmamk_f32 v58, v58, 0xbdd2d3e8, v209
	v_fmamk_f32 v59, v59, 0xbdd2d3e8, v209
	v_mul_f32_e32 v56, v52, v56
	v_mul_f32_e32 v57, v53, v57
	v_mul_f32_e32 v58, v54, v58
	v_mul_f32_e32 v59, v55, v59
	v_exp_f32_e32 v56, v56
	v_exp_f32_e32 v57, v57
	v_exp_f32_e32 v58, v58
	v_exp_f32_e32 v59, v59
	v_add_f32_e32 v56, 1.0, v56
	v_add_f32_e32 v57, 1.0, v57
	v_add_f32_e32 v58, 1.0, v58
	v_add_f32_e32 v59, 1.0, v59
	v_rcp_f32_e32 v56, v56
	v_rcp_f32_e32 v57, v57
	v_rcp_f32_e32 v58, v58
	v_rcp_f32_e32 v59, v59
	v_pk_mul_f32 v[52:53], v[52:53], v[56:57]
	v_mul_f32_e32 v56, v48, v48
	v_pk_mul_f32 v[54:55], v[54:55], v[58:59]
	v_mul_f32_e32 v57, v49, v49
	v_mul_f32_e32 v58, v50, v50
	v_mul_f32_e32 v59, v51, v51
	v_fmamk_f32 v56, v56, 0xbdd2d3e8, v209
	v_fmamk_f32 v57, v57, 0xbdd2d3e8, v209
	v_fmamk_f32 v58, v58, 0xbdd2d3e8, v209
	v_fmamk_f32 v59, v59, 0xbdd2d3e8, v209
	v_mul_f32_e32 v56, v48, v56
	v_mul_f32_e32 v57, v49, v57
	v_mul_f32_e32 v58, v50, v58
	v_mul_f32_e32 v59, v51, v59
	v_exp_f32_e32 v56, v56
	v_exp_f32_e32 v57, v57
	v_exp_f32_e32 v58, v58
	v_exp_f32_e32 v59, v59
	v_add_f32_e32 v56, 1.0, v56
	v_add_f32_e32 v57, 1.0, v57
	v_add_f32_e32 v58, 1.0, v58
	v_add_f32_e32 v59, 1.0, v59
	v_rcp_f32_e32 v56, v56
	v_rcp_f32_e32 v57, v57
	v_rcp_f32_e32 v58, v58
	v_rcp_f32_e32 v59, v59
	v_pk_mul_f32 v[48:49], v[48:49], v[56:57]
	v_pk_mul_f32 v[50:51], v[50:51], v[58:59]
.LBB0_521:
	s_mov_b64 s[16:17], 0x20000
	v_lshl_add_u64 v[56:57], v[64:65], 0, s[16:17]
	v_cvt_pk_bf16_f32 v52, v52, v53
	v_cvt_pk_bf16_f32 v53, v54, v55
	v_cvt_pk_bf16_f32 v54, v48, v49
	v_cvt_pk_bf16_f32 v55, v50, v51
	s_and_b64 vcc, exec, s[8:9]
	global_store_dwordx4 v[56:57], v[52:55], off offset:256 nt
	s_cbranch_vccnz .LBB0_523
	v_mul_f32_e32 v48, v44, v44
	v_mul_f32_e32 v49, v45, v45
	v_mul_f32_e32 v50, v46, v46
	v_mul_f32_e32 v51, v47, v47
	v_fmamk_f32 v48, v48, 0xbdd2d3e8, v209
	v_fmamk_f32 v49, v49, 0xbdd2d3e8, v209
	v_fmamk_f32 v50, v50, 0xbdd2d3e8, v209
	v_fmamk_f32 v51, v51, 0xbdd2d3e8, v209
	v_mul_f32_e32 v48, v44, v48
	v_mul_f32_e32 v49, v45, v49
	v_mul_f32_e32 v50, v46, v50
	v_mul_f32_e32 v51, v47, v51
	v_exp_f32_e32 v48, v48
	v_exp_f32_e32 v49, v49
	v_exp_f32_e32 v50, v50
	v_exp_f32_e32 v51, v51
	v_add_f32_e32 v48, 1.0, v48
	v_add_f32_e32 v49, 1.0, v49
	v_add_f32_e32 v50, 1.0, v50
	v_add_f32_e32 v51, 1.0, v51
	v_rcp_f32_e32 v48, v48
	v_rcp_f32_e32 v49, v49
	v_rcp_f32_e32 v50, v50
	v_rcp_f32_e32 v51, v51
	v_pk_mul_f32 v[44:45], v[44:45], v[48:49]
	v_mul_f32_e32 v48, v40, v40
	v_pk_mul_f32 v[46:47], v[46:47], v[50:51]
	v_mul_f32_e32 v49, v41, v41
	v_mul_f32_e32 v50, v42, v42
	v_mul_f32_e32 v51, v43, v43
	v_fmamk_f32 v48, v48, 0xbdd2d3e8, v209
	v_fmamk_f32 v49, v49, 0xbdd2d3e8, v209
	v_fmamk_f32 v50, v50, 0xbdd2d3e8, v209
	v_fmamk_f32 v51, v51, 0xbdd2d3e8, v209
	v_mul_f32_e32 v48, v40, v48
	v_mul_f32_e32 v49, v41, v49
	v_mul_f32_e32 v50, v42, v50
	v_mul_f32_e32 v51, v43, v51
	v_exp_f32_e32 v48, v48
	v_exp_f32_e32 v49, v49
	v_exp_f32_e32 v50, v50
	v_exp_f32_e32 v51, v51
	v_add_f32_e32 v48, 1.0, v48
	v_add_f32_e32 v49, 1.0, v49
	v_add_f32_e32 v50, 1.0, v50
	v_add_f32_e32 v51, 1.0, v51
	v_rcp_f32_e32 v48, v48
	v_rcp_f32_e32 v49, v49
	v_rcp_f32_e32 v50, v50
	v_rcp_f32_e32 v51, v51
	v_pk_mul_f32 v[40:41], v[40:41], v[48:49]
	v_pk_mul_f32 v[42:43], v[42:43], v[50:51]
.LBB0_523:
	v_lshlrev_b64 v[48:49], 10, v[190:191]
	v_lshl_add_u64 v[48:49], v[128:129], 0, v[48:49]
	v_cvt_pk_bf16_f32 v44, v44, v45
	v_cvt_pk_bf16_f32 v45, v46, v47
	v_cvt_pk_bf16_f32 v46, v40, v41
	v_add_co_u32_e32 v40, vcc, 0x24000, v48
	v_cvt_pk_bf16_f32 v47, v42, v43
	s_nop 0
	v_addc_co_u32_e32 v41, vcc, 0, v49, vcc
	s_and_b64 vcc, exec, s[8:9]
	global_store_dwordx4 v[40:41], v[44:47], off nt
	s_cbranch_vccnz .LBB0_525
	v_mul_f32_e32 v40, v36, v36
	v_mul_f32_e32 v41, v37, v37
	v_mul_f32_e32 v42, v38, v38
	v_mul_f32_e32 v43, v39, v39
	v_fmamk_f32 v40, v40, 0xbdd2d3e8, v209
	v_fmamk_f32 v41, v41, 0xbdd2d3e8, v209
	v_fmamk_f32 v42, v42, 0xbdd2d3e8, v209
	v_fmamk_f32 v43, v43, 0xbdd2d3e8, v209
	v_mul_f32_e32 v40, v36, v40
	v_mul_f32_e32 v41, v37, v41
	v_mul_f32_e32 v42, v38, v42
	v_mul_f32_e32 v43, v39, v43
	v_exp_f32_e32 v40, v40
	v_exp_f32_e32 v41, v41
	v_exp_f32_e32 v42, v42
	v_exp_f32_e32 v43, v43
	v_add_f32_e32 v40, 1.0, v40
	v_add_f32_e32 v41, 1.0, v41
	v_add_f32_e32 v42, 1.0, v42
	v_add_f32_e32 v43, 1.0, v43
	v_rcp_f32_e32 v40, v40
	v_rcp_f32_e32 v41, v41
	v_rcp_f32_e32 v42, v42
	v_rcp_f32_e32 v43, v43
	v_pk_mul_f32 v[36:37], v[36:37], v[40:41]
	v_mul_f32_e32 v40, v32, v32
	v_pk_mul_f32 v[38:39], v[38:39], v[42:43]
	v_mul_f32_e32 v41, v33, v33
	v_mul_f32_e32 v42, v34, v34
	v_mul_f32_e32 v43, v35, v35
	v_fmamk_f32 v40, v40, 0xbdd2d3e8, v209
	v_fmamk_f32 v41, v41, 0xbdd2d3e8, v209
	v_fmamk_f32 v42, v42, 0xbdd2d3e8, v209
	v_fmamk_f32 v43, v43, 0xbdd2d3e8, v209
	v_mul_f32_e32 v40, v32, v40
	v_mul_f32_e32 v41, v33, v41
	v_mul_f32_e32 v42, v34, v42
	v_mul_f32_e32 v43, v35, v43
	v_exp_f32_e32 v40, v40
	v_exp_f32_e32 v41, v41
	v_exp_f32_e32 v42, v42
	v_exp_f32_e32 v43, v43
	v_add_f32_e32 v40, 1.0, v40
	v_add_f32_e32 v41, 1.0, v41
	v_add_f32_e32 v42, 1.0, v42
	v_add_f32_e32 v43, 1.0, v43
	v_rcp_f32_e32 v40, v40
	v_rcp_f32_e32 v41, v41
	v_rcp_f32_e32 v42, v42
	v_rcp_f32_e32 v43, v43
	v_pk_mul_f32 v[32:33], v[32:33], v[40:41]
	v_pk_mul_f32 v[34:35], v[34:35], v[42:43]
.LBB0_525:
	s_mov_b64 s[16:17], 0x24000
	v_lshl_add_u64 v[40:41], v[48:49], 0, s[16:17]
	v_cvt_pk_bf16_f32 v36, v36, v37
	v_cvt_pk_bf16_f32 v37, v38, v39
	v_cvt_pk_bf16_f32 v38, v32, v33
	v_cvt_pk_bf16_f32 v39, v34, v35
	s_and_b64 vcc, exec, s[8:9]
	global_store_dwordx4 v[40:41], v[36:39], off offset:256 nt
	s_cbranch_vccnz .LBB0_527
	v_mul_f32_e32 v32, v28, v28
	v_mul_f32_e32 v33, v29, v29
	v_mul_f32_e32 v34, v30, v30
	v_mul_f32_e32 v35, v31, v31
	v_fmamk_f32 v32, v32, 0xbdd2d3e8, v209
	v_fmamk_f32 v33, v33, 0xbdd2d3e8, v209
	v_fmamk_f32 v34, v34, 0xbdd2d3e8, v209
	v_fmamk_f32 v35, v35, 0xbdd2d3e8, v209
	v_mul_f32_e32 v32, v28, v32
	v_mul_f32_e32 v33, v29, v33
	v_mul_f32_e32 v34, v30, v34
	v_mul_f32_e32 v35, v31, v35
	v_exp_f32_e32 v32, v32
	v_exp_f32_e32 v33, v33
	v_exp_f32_e32 v34, v34
	v_exp_f32_e32 v35, v35
	v_add_f32_e32 v32, 1.0, v32
	v_add_f32_e32 v33, 1.0, v33
	v_add_f32_e32 v34, 1.0, v34
	v_add_f32_e32 v35, 1.0, v35
	v_rcp_f32_e32 v32, v32
	v_rcp_f32_e32 v33, v33
	v_rcp_f32_e32 v34, v34
	v_rcp_f32_e32 v35, v35
	v_pk_mul_f32 v[28:29], v[28:29], v[32:33]
	v_mul_f32_e32 v32, v24, v24
	v_pk_mul_f32 v[30:31], v[30:31], v[34:35]
	v_mul_f32_e32 v33, v25, v25
	v_mul_f32_e32 v34, v26, v26
	v_mul_f32_e32 v35, v27, v27
	v_fmamk_f32 v32, v32, 0xbdd2d3e8, v209
	v_fmamk_f32 v33, v33, 0xbdd2d3e8, v209
	v_fmamk_f32 v34, v34, 0xbdd2d3e8, v209
	v_fmamk_f32 v35, v35, 0xbdd2d3e8, v209
	v_mul_f32_e32 v32, v24, v32
	v_mul_f32_e32 v33, v25, v33
	v_mul_f32_e32 v34, v26, v34
	v_mul_f32_e32 v35, v27, v35
	v_exp_f32_e32 v32, v32
	v_exp_f32_e32 v33, v33
	v_exp_f32_e32 v34, v34
	v_exp_f32_e32 v35, v35
	v_add_f32_e32 v32, 1.0, v32
	v_add_f32_e32 v33, 1.0, v33
	v_add_f32_e32 v34, 1.0, v34
	v_add_f32_e32 v35, 1.0, v35
	v_rcp_f32_e32 v32, v32
	v_rcp_f32_e32 v33, v33
	v_rcp_f32_e32 v34, v34
	v_rcp_f32_e32 v35, v35
	v_pk_mul_f32 v[24:25], v[24:25], v[32:33]
	v_pk_mul_f32 v[26:27], v[26:27], v[34:35]
.LBB0_527:
	v_lshlrev_b64 v[32:33], 10, v[190:191]
	v_lshl_add_u64 v[32:33], v[128:129], 0, v[32:33]
	v_cvt_pk_bf16_f32 v28, v28, v29
	v_cvt_pk_bf16_f32 v29, v30, v31
	v_cvt_pk_bf16_f32 v30, v24, v25
	v_add_co_u32_e32 v24, vcc, 0x28000, v32
	v_cvt_pk_bf16_f32 v31, v26, v27
	s_nop 0
	v_addc_co_u32_e32 v25, vcc, 0, v33, vcc
	s_and_b64 vcc, exec, s[8:9]
	global_store_dwordx4 v[24:25], v[28:31], off nt
	s_cbranch_vccnz .LBB0_529
	v_mul_f32_e32 v24, v20, v20
	v_mul_f32_e32 v25, v21, v21
	v_mul_f32_e32 v26, v22, v22
	v_mul_f32_e32 v27, v23, v23
	v_fmamk_f32 v24, v24, 0xbdd2d3e8, v209
	v_fmamk_f32 v25, v25, 0xbdd2d3e8, v209
	v_fmamk_f32 v26, v26, 0xbdd2d3e8, v209
	v_fmamk_f32 v27, v27, 0xbdd2d3e8, v209
	v_mul_f32_e32 v24, v20, v24
	v_mul_f32_e32 v25, v21, v25
	v_mul_f32_e32 v26, v22, v26
	v_mul_f32_e32 v27, v23, v27
	v_exp_f32_e32 v24, v24
	v_exp_f32_e32 v25, v25
	v_exp_f32_e32 v26, v26
	v_exp_f32_e32 v27, v27
	v_add_f32_e32 v24, 1.0, v24
	v_add_f32_e32 v25, 1.0, v25
	v_add_f32_e32 v26, 1.0, v26
	v_add_f32_e32 v27, 1.0, v27
	v_rcp_f32_e32 v24, v24
	v_rcp_f32_e32 v25, v25
	v_rcp_f32_e32 v26, v26
	v_rcp_f32_e32 v27, v27
	v_pk_mul_f32 v[20:21], v[20:21], v[24:25]
	v_mul_f32_e32 v24, v16, v16
	v_pk_mul_f32 v[22:23], v[22:23], v[26:27]
	v_mul_f32_e32 v25, v17, v17
	v_mul_f32_e32 v26, v18, v18
	v_mul_f32_e32 v27, v19, v19
	v_fmamk_f32 v24, v24, 0xbdd2d3e8, v209
	v_fmamk_f32 v25, v25, 0xbdd2d3e8, v209
	v_fmamk_f32 v26, v26, 0xbdd2d3e8, v209
	v_fmamk_f32 v27, v27, 0xbdd2d3e8, v209
	v_mul_f32_e32 v24, v16, v24
	v_mul_f32_e32 v25, v17, v25
	v_mul_f32_e32 v26, v18, v26
	v_mul_f32_e32 v27, v19, v27
	v_exp_f32_e32 v24, v24
	v_exp_f32_e32 v25, v25
	v_exp_f32_e32 v26, v26
	v_exp_f32_e32 v27, v27
	v_add_f32_e32 v24, 1.0, v24
	v_add_f32_e32 v25, 1.0, v25
	v_add_f32_e32 v26, 1.0, v26
	v_add_f32_e32 v27, 1.0, v27
	v_rcp_f32_e32 v24, v24
	v_rcp_f32_e32 v25, v25
	v_rcp_f32_e32 v26, v26
	v_rcp_f32_e32 v27, v27
	v_pk_mul_f32 v[16:17], v[16:17], v[24:25]
	v_pk_mul_f32 v[18:19], v[18:19], v[26:27]
.LBB0_529:
	s_mov_b64 s[16:17], 0x28000
	v_lshl_add_u64 v[24:25], v[32:33], 0, s[16:17]
	v_cvt_pk_bf16_f32 v20, v20, v21
	v_cvt_pk_bf16_f32 v21, v22, v23
	v_cvt_pk_bf16_f32 v22, v16, v17
	v_cvt_pk_bf16_f32 v23, v18, v19
	s_and_b64 vcc, exec, s[8:9]
	global_store_dwordx4 v[24:25], v[20:23], off offset:256 nt
	s_cbranch_vccnz .LBB0_531
	v_mul_f32_e32 v16, v12, v12
	v_mul_f32_e32 v17, v13, v13
	v_mul_f32_e32 v18, v14, v14
	v_mul_f32_e32 v19, v15, v15
	v_fmamk_f32 v16, v16, 0xbdd2d3e8, v209
	v_fmamk_f32 v17, v17, 0xbdd2d3e8, v209
	v_fmamk_f32 v18, v18, 0xbdd2d3e8, v209
	v_fmamk_f32 v19, v19, 0xbdd2d3e8, v209
	v_mul_f32_e32 v16, v12, v16
	v_mul_f32_e32 v17, v13, v17
	v_mul_f32_e32 v18, v14, v18
	v_mul_f32_e32 v19, v15, v19
	v_exp_f32_e32 v16, v16
	v_exp_f32_e32 v17, v17
	v_exp_f32_e32 v18, v18
	v_exp_f32_e32 v19, v19
	v_add_f32_e32 v16, 1.0, v16
	v_add_f32_e32 v17, 1.0, v17
	v_add_f32_e32 v18, 1.0, v18
	v_add_f32_e32 v19, 1.0, v19
	v_rcp_f32_e32 v16, v16
	v_rcp_f32_e32 v17, v17
	v_rcp_f32_e32 v18, v18
	v_rcp_f32_e32 v19, v19
	v_pk_mul_f32 v[12:13], v[12:13], v[16:17]
	v_mul_f32_e32 v16, v8, v8
	v_pk_mul_f32 v[14:15], v[14:15], v[18:19]
	v_mul_f32_e32 v17, v9, v9
	v_mul_f32_e32 v18, v10, v10
	v_mul_f32_e32 v19, v11, v11
	v_fmamk_f32 v16, v16, 0xbdd2d3e8, v209
	v_fmamk_f32 v17, v17, 0xbdd2d3e8, v209
	v_fmamk_f32 v18, v18, 0xbdd2d3e8, v209
	v_fmamk_f32 v19, v19, 0xbdd2d3e8, v209
	v_mul_f32_e32 v16, v8, v16
	v_mul_f32_e32 v17, v9, v17
	v_mul_f32_e32 v18, v10, v18
	v_mul_f32_e32 v19, v11, v19
	v_exp_f32_e32 v16, v16
	v_exp_f32_e32 v17, v17
	v_exp_f32_e32 v18, v18
	v_exp_f32_e32 v19, v19
	v_add_f32_e32 v16, 1.0, v16
	v_add_f32_e32 v17, 1.0, v17
	v_add_f32_e32 v18, 1.0, v18
	v_add_f32_e32 v19, 1.0, v19
	v_rcp_f32_e32 v16, v16
	v_rcp_f32_e32 v17, v17
	v_rcp_f32_e32 v18, v18
	v_rcp_f32_e32 v19, v19
	v_pk_mul_f32 v[8:9], v[8:9], v[16:17]
	v_pk_mul_f32 v[10:11], v[10:11], v[18:19]
.LBB0_531:
	v_lshlrev_b64 v[16:17], 10, v[190:191]
	v_lshl_add_u64 v[16:17], v[128:129], 0, v[16:17]
	v_cvt_pk_bf16_f32 v12, v12, v13
	v_cvt_pk_bf16_f32 v13, v14, v15
	v_cvt_pk_bf16_f32 v14, v8, v9
	v_add_co_u32_e32 v8, vcc, 0x2c000, v16
	v_cvt_pk_bf16_f32 v15, v10, v11
	s_nop 0
	v_addc_co_u32_e32 v9, vcc, 0, v17, vcc
	s_and_b64 vcc, exec, s[8:9]
	global_store_dwordx4 v[8:9], v[12:15], off nt
	s_cbranch_vccnz .LBB0_533
	v_mul_f32_e32 v8, v4, v4
	v_mul_f32_e32 v9, v5, v5
	v_mul_f32_e32 v10, v6, v6
	v_mul_f32_e32 v11, v7, v7
	v_fmamk_f32 v8, v8, 0xbdd2d3e8, v209
	v_fmamk_f32 v9, v9, 0xbdd2d3e8, v209
	v_fmamk_f32 v10, v10, 0xbdd2d3e8, v209
	v_fmamk_f32 v11, v11, 0xbdd2d3e8, v209
	v_mul_f32_e32 v8, v4, v8
	v_mul_f32_e32 v9, v5, v9
	v_mul_f32_e32 v10, v6, v10
	v_mul_f32_e32 v11, v7, v11
	v_exp_f32_e32 v8, v8
	v_exp_f32_e32 v9, v9
	v_exp_f32_e32 v10, v10
	v_exp_f32_e32 v11, v11
	v_add_f32_e32 v8, 1.0, v8
	v_add_f32_e32 v9, 1.0, v9
	v_add_f32_e32 v10, 1.0, v10
	v_add_f32_e32 v11, 1.0, v11
	v_rcp_f32_e32 v8, v8
	v_rcp_f32_e32 v9, v9
	v_rcp_f32_e32 v10, v10
	v_rcp_f32_e32 v11, v11
	v_pk_mul_f32 v[4:5], v[4:5], v[8:9]
	v_mul_f32_e32 v8, v0, v0
	v_pk_mul_f32 v[6:7], v[6:7], v[10:11]
	v_mul_f32_e32 v9, v1, v1
	v_mul_f32_e32 v10, v2, v2
	v_mul_f32_e32 v11, v3, v3
	v_fmamk_f32 v8, v8, 0xbdd2d3e8, v209
	v_fmamk_f32 v9, v9, 0xbdd2d3e8, v209
	v_fmamk_f32 v10, v10, 0xbdd2d3e8, v209
	v_fmamk_f32 v11, v11, 0xbdd2d3e8, v209
	v_mul_f32_e32 v8, v0, v8
	v_mul_f32_e32 v9, v1, v9
	v_mul_f32_e32 v10, v2, v10
	v_mul_f32_e32 v11, v3, v11
	v_exp_f32_e32 v8, v8
	v_exp_f32_e32 v9, v9
	v_exp_f32_e32 v10, v10
	v_exp_f32_e32 v11, v11
	v_add_f32_e32 v8, 1.0, v8
	v_add_f32_e32 v9, 1.0, v9
	v_add_f32_e32 v10, 1.0, v10
	v_add_f32_e32 v11, 1.0, v11
	v_rcp_f32_e32 v8, v8
	v_rcp_f32_e32 v9, v9
	v_rcp_f32_e32 v10, v10
	v_rcp_f32_e32 v11, v11
	v_pk_mul_f32 v[0:1], v[0:1], v[8:9]
	v_pk_mul_f32 v[2:3], v[2:3], v[10:11]
.LBB0_533:
	s_mov_b64 s[8:9], 0x2c000
	v_lshl_add_u64 v[8:9], v[16:17], 0, s[8:9]
	v_cvt_pk_bf16_f32 v4, v4, v5
	v_cvt_pk_bf16_f32 v5, v6, v7
	v_cvt_pk_bf16_f32 v6, v0, v1
	v_cvt_pk_bf16_f32 v7, v2, v3
	global_store_dwordx4 v[8:9], v[4:7], off offset:256 nt
	s_andn2_b64 vcc, exec, s[6:7]
	s_mov_b64 s[6:7], -1
	s_cbranch_vccnz .LBB0_479
